# v18 + SwiGLU epilogue: neighbouring lanes exchange values through DPP and store packed dwords (16 global_store_dword instead of 32 global_store_short per wave tile)
# speedup vs baseline: 1.0023x; 1.0023x over previous
.LBB0_56:
	ds_read_b128 v[188:191], v160
	ds_read_b128 v[192:195], v160 offset:32
	ds_read_b128 v[196:199], v161 offset:36864
	ds_read_b128 v[200:203], v161 offset:36896
	ds_read_b128 v[204:207], v160 offset:4608
	ds_read_b128 v[208:211], v160 offset:4640
	ds_read_b128 v[212:215], v161 offset:41472
	ds_read_b128 v[216:219], v161 offset:41504
	s_add_i32 s42, s43, 2
	s_waitcnt lgkmcnt(5)
	v_mfma_f32_32x32x16_bf16 v[50:65], v[188:191], v[196:199], v[50:65]
	s_waitcnt vmcnt(15)
	ds_write_b128 v184, v[66:69] offset:18432
	s_cmp_lt_u32 s42, 13
	s_cselect_b64 s[46:47], -1, 0
	s_and_b64 s[20:21], s[46:47], exec
	s_cselect_b32 s20, 0, 0x1fffff0
	s_add_i32 s20, s20, s43
	s_lshl_b32 s45, s20, 7
	s_waitcnt lgkmcnt(2)
	v_mfma_f32_32x32x16_bf16 v[34:49], v[188:191], v[212:215], v[34:49]
	s_waitcnt vmcnt(14)
	ds_write_b128 v184, v[74:77] offset:55296
	s_add_i32 s50, s45, 0x280
	s_and_b64 s[20:21], s[46:47], exec
	s_cselect_b32 s21, s31, s38
	s_cselect_b32 s20, s40, s37
	s_and_b32 s21, s21, 0xffff
	s_and_b64 s[46:47], s[46:47], exec
	s_waitcnt lgkmcnt(5)
	v_mfma_f32_32x32x16_bf16 v[16:31], v[204:207], v[196:199], v[16:31]
	s_waitcnt vmcnt(13)
	ds_write_b128 v185, v[70:73] offset:18432
	s_cselect_b32 s46, s36, s41
	s_cselect_b32 s52, s44, s39
	s_and_b32 s53, s46, 0xffff
	s_mov_b32 s54, s22
	s_mov_b32 s55, s23
	s_add_i32 s46, s45, 0x10280
	s_waitcnt lgkmcnt(4)
	v_mfma_f32_32x32x16_bf16 v[0:15], v[204:207], v[212:215], v[0:15]
	s_waitcnt vmcnt(12)
	ds_write_b128 v185, v[82:85] offset:55296
	s_waitcnt lgkmcnt(8)
	v_mfma_f32_32x32x16_bf16 v[50:65], v[192:195], v[200:203], v[50:65]
	ds_read_b128 v[220:223], v160 offset:64
	ds_read_b128 v[142:145], v160 offset:96
	s_waitcnt vmcnt(11)
	ds_write_b128 v186, v[78:81] offset:18432
	s_waitcnt lgkmcnt(7)
	v_mfma_f32_32x32x16_bf16 v[34:49], v[192:195], v[216:219], v[34:49]
	ds_read_b128 v[154:157], v161 offset:36928
	ds_read_b128 v[138:141], v161 offset:36960
	s_waitcnt vmcnt(10)
	ds_write_b128 v186, v[90:93] offset:55296
	s_waitcnt lgkmcnt(12)
	v_mfma_f32_32x32x16_bf16 v[16:31], v[208:211], v[200:203], v[16:31]
	ds_read_b128 v[146:149], v160 offset:4672
	ds_read_b128 v[130:133], v160 offset:4704
	s_waitcnt vmcnt(9)
	ds_write_b128 v187, v[86:89] offset:18432
	s_waitcnt lgkmcnt(13)
	v_mfma_f32_32x32x16_bf16 v[0:15], v[208:211], v[216:219], v[0:15]
	ds_read_b128 v[150:153], v161 offset:41536
	ds_read_b128 v[134:137], v161 offset:41568
	s_waitcnt vmcnt(8)
	ds_write_b128 v187, v[94:97] offset:55296
	s_waitcnt lgkmcnt(8)
	v_mfma_f32_32x32x16_bf16 v[50:65], v[220:223], v[154:157], v[50:65]
	buffer_load_dwordx4 v[66:69], v32, s[20:23], s50 offen
	s_waitcnt lgkmcnt(2)
	v_mfma_f32_32x32x16_bf16 v[34:49], v[220:223], v[150:153], v[34:49]
	buffer_load_dwordx4 v[74:77], v32, s[52:55], s50 offen
	s_waitcnt lgkmcnt(5)
	v_mfma_f32_32x32x16_bf16 v[16:31], v[146:149], v[154:157], v[16:31]
	buffer_load_dwordx4 v[70:73], v32, s[20:23], s46 offen
	s_waitcnt lgkmcnt(2)
	v_mfma_f32_32x32x16_bf16 v[0:15], v[146:149], v[150:153], v[0:15]
	buffer_load_dwordx4 v[82:85], v32, s[52:55], s46 offen
	s_add_i32 s46, s45, 0x20280
	s_add_i32 s45, s45, 0x30280
	s_waitcnt lgkmcnt(7)
	v_mfma_f32_32x32x16_bf16 v[50:65], v[142:145], v[138:141], v[50:65]
	buffer_load_dwordx4 v[78:81], v32, s[20:23], s46 offen
	s_waitcnt lgkmcnt(1)
	v_mfma_f32_32x32x16_bf16 v[34:49], v[142:145], v[134:137], v[34:49]
	buffer_load_dwordx4 v[90:93], v32, s[52:55], s46 offen
	s_waitcnt lgkmcnt(4)
	v_mfma_f32_32x32x16_bf16 v[16:31], v[130:133], v[138:141], v[16:31]
	buffer_load_dwordx4 v[86:89], v32, s[20:23], s45 offen
	s_waitcnt lgkmcnt(1)
	v_mfma_f32_32x32x16_bf16 v[0:15], v[130:133], v[134:137], v[0:15]
	buffer_load_dwordx4 v[94:97], v32, s[52:55], s45 offen
	s_waitcnt lgkmcnt(0)
	s_barrier
	ds_read_b128 v[188:191], v160 offset:18432
	ds_read_b128 v[192:195], v160 offset:18464
	ds_read_b128 v[196:199], v161 offset:55296
	ds_read_b128 v[200:203], v161 offset:55328
	ds_read_b128 v[204:207], v160 offset:23040
	ds_read_b128 v[208:211], v160 offset:23072
	ds_read_b128 v[212:215], v161 offset:59904
	ds_read_b128 v[216:219], v161 offset:59936
	s_waitcnt lgkmcnt(5)
	v_mfma_f32_32x32x16_bf16 v[50:65], v[188:191], v[196:199], v[50:65]
	s_waitcnt vmcnt(15)
	ds_write_b128 v184, v[98:101]
	s_cmp_lt_u32 s42, 12
	s_cselect_b64 s[46:47], -1, 0
	s_and_b64 s[20:21], s[46:47], exec
	s_cselect_b32 s20, 0, 0x1fffff0
	s_add_i32 s20, s20, s43
	s_lshl_b32 s43, s20, 7
	s_waitcnt lgkmcnt(2)
	v_mfma_f32_32x32x16_bf16 v[34:49], v[188:191], v[212:215], v[34:49]
	s_waitcnt vmcnt(14)
	ds_write_b128 v184, v[106:109] offset:36864
	s_add_i32 s45, s43, 0x300
	s_and_b64 s[20:21], s[46:47], exec
	s_cselect_b32 s21, s31, s38
	s_cselect_b32 s20, s40, s37
	s_and_b32 s21, s21, 0xffff
	s_and_b64 s[46:47], s[46:47], exec
	s_waitcnt lgkmcnt(5)
	v_mfma_f32_32x32x16_bf16 v[16:31], v[204:207], v[196:199], v[16:31]
	s_waitcnt vmcnt(13)
	ds_write_b128 v185, v[102:105]
	s_cselect_b32 s46, s36, s41
	s_cselect_b32 s52, s44, s39
	s_and_b32 s53, s46, 0xffff
	s_waitcnt lgkmcnt(4)
	v_mfma_f32_32x32x16_bf16 v[0:15], v[204:207], v[212:215], v[0:15]
	s_waitcnt vmcnt(12)
	ds_write_b128 v185, v[114:117] offset:36864
	s_waitcnt lgkmcnt(8)
	v_mfma_f32_32x32x16_bf16 v[50:65], v[192:195], v[200:203], v[50:65]
	ds_read_b128 v[220:223], v160 offset:18496
	ds_read_b128 v[142:145], v160 offset:18528
	s_waitcnt vmcnt(11)
	ds_write_b128 v186, v[110:113]
	s_waitcnt lgkmcnt(7)
	v_mfma_f32_32x32x16_bf16 v[34:49], v[192:195], v[216:219], v[34:49]
	ds_read_b128 v[154:157], v161 offset:55360
	ds_read_b128 v[138:141], v161 offset:55392
	s_waitcnt vmcnt(10)
	ds_write_b128 v186, v[122:125] offset:36864
	s_waitcnt lgkmcnt(12)
	v_mfma_f32_32x32x16_bf16 v[16:31], v[208:211], v[200:203], v[16:31]
	ds_read_b128 v[146:149], v160 offset:23104
	ds_read_b128 v[130:133], v160 offset:23136
	s_waitcnt vmcnt(9)
	ds_write_b128 v187, v[118:121]
	s_waitcnt lgkmcnt(13)
	v_mfma_f32_32x32x16_bf16 v[0:15], v[208:211], v[216:219], v[0:15]
	ds_read_b128 v[150:153], v161 offset:59968
	ds_read_b128 v[134:137], v161 offset:60000
	s_waitcnt vmcnt(8)
	ds_write_b128 v187, v[126:129] offset:36864
	s_waitcnt lgkmcnt(8)
	v_mfma_f32_32x32x16_bf16 v[50:65], v[220:223], v[154:157], v[50:65]
	buffer_load_dwordx4 v[98:101], v32, s[20:23], s45 offen
	s_waitcnt lgkmcnt(2)
	v_mfma_f32_32x32x16_bf16 v[34:49], v[220:223], v[150:153], v[34:49]
	buffer_load_dwordx4 v[106:109], v32, s[52:55], s45 offen
	s_add_i32 s45, s43, 0x10300
	s_waitcnt lgkmcnt(5)
	v_mfma_f32_32x32x16_bf16 v[16:31], v[146:149], v[154:157], v[16:31]
	buffer_load_dwordx4 v[102:105], v32, s[20:23], s45 offen
	s_waitcnt lgkmcnt(2)
	v_mfma_f32_32x32x16_bf16 v[0:15], v[146:149], v[150:153], v[0:15]
	buffer_load_dwordx4 v[114:117], v32, s[52:55], s45 offen
	s_add_i32 s45, s43, 0x20300
	s_add_i32 s43, s43, 0x30300
	s_waitcnt lgkmcnt(7)
	v_mfma_f32_32x32x16_bf16 v[50:65], v[142:145], v[138:141], v[50:65]
	buffer_load_dwordx4 v[110:113], v32, s[20:23], s45 offen
	s_waitcnt lgkmcnt(1)
	v_mfma_f32_32x32x16_bf16 v[34:49], v[142:145], v[134:137], v[34:49]
	buffer_load_dwordx4 v[122:125], v32, s[52:55], s45 offen
	s_waitcnt lgkmcnt(4)
	v_mfma_f32_32x32x16_bf16 v[16:31], v[130:133], v[138:141], v[16:31]
	buffer_load_dwordx4 v[118:121], v32, s[20:23], s43 offen
	s_waitcnt lgkmcnt(1)
	v_mfma_f32_32x32x16_bf16 v[0:15], v[130:133], v[134:137], v[0:15]
	buffer_load_dwordx4 v[126:129], v32, s[52:55], s43 offen
	s_cmp_gt_u32 s42, 13
	s_mov_b32 s43, s42
	s_waitcnt lgkmcnt(0)
	s_barrier
	s_cbranch_scc0 .LBB0_56
	v_add_u32_e32 v32, s28, v183
	s_lshl_b32 s20, s30, 6
	v_lshlrev_b32_e32 v130, 5, v181
	v_lshl_or_b32 v32, v182, 2, v32
	v_mul_lo_u32 v32, v32, s97
	v_or3_b32 v130, v130, s20, v180
	v_add_lshl_u32 v32, v130, v32, 1
	v_and_b32_e32 v204, 1, v180
	v_mul_u32_u24_e32 v204, 0x15fe, v204
	v_add_u32_e32 v32, v32, v204
	v_readlane_b32 s20, v235, 34
	v_readlane_b32 s21, v235, 35
	v_readlane_b32 s52, v233, 61
	v_readlane_b32 s62, v232, 7
	v_readlane_b32 s63, v232, 8
	s_mov_b32 vcc_lo, 0x55555555
	s_mov_b32 vcc_hi, 0x55555555
	s_mov_b32 s37, s29
	v_readlane_b32 s53, v233, 62
	v_readlane_b32 s56, v232, 1
	v_readlane_b32 s57, v232, 2
	v_readlane_b32 s58, v232, 3
	v_readlane_b32 s59, v232, 4
	v_readlane_b32 s60, v232, 5
	v_readlane_b32 s61, v232, 6
	v_readlane_b32 s64, v232, 9
	v_readlane_b32 s65, v232, 10
	v_readlane_b32 s66, v232, 11
	v_readlane_b32 s67, v232, 12
	v_readlane_b32 s63, v235, 21
	v_readlane_b32 s62, v232, 31
	v_readlane_b32 s54, v233, 63
	v_readlane_b32 s55, v232, 0
	v_mul_f32_e32 v188, 0xbfb8aa3b, v50
	v_mul_f32_e32 v189, 0xbfb8aa3b, v51
	v_mul_f32_e32 v190, 0xbfb8aa3b, v52
	v_mul_f32_e32 v191, 0xbfb8aa3b, v53
	v_exp_f32_e32 v188, v188
	v_exp_f32_e32 v189, v189
	v_exp_f32_e32 v190, v190
	v_exp_f32_e32 v191, v191
	v_mov_b32_e32 v200, v32
	v_add_u32_e32 v201, 0x2c00, v32
	v_add_f32_e32 v188, 1.0, v188
	v_add_f32_e32 v189, 1.0, v189
	v_add_f32_e32 v190, 1.0, v190
	v_add_f32_e32 v191, 1.0, v191
	v_rcp_f32_e32 v188, v188
	v_rcp_f32_e32 v189, v189
	v_rcp_f32_e32 v190, v190
	v_rcp_f32_e32 v191, v191
	v_mul_f32_e32 v188, v50, v188
	v_mul_f32_e32 v189, v51, v189
	v_mul_f32_e32 v190, v52, v190
	v_mul_f32_e32 v191, v53, v191
	v_mul_f32_e32 v188, v34, v188
	v_mul_f32_e32 v189, v35, v189
	v_mul_f32_e32 v190, v36, v190
	v_mul_f32_e32 v191, v37, v191
	v_cndmask_b32_e32 v204, v188, v189, vcc
	v_cndmask_b32_e32 v205, v190, v191, vcc
	s_nop 1
	v_mov_b32_dpp v204, v204 quad_perm:[1,0,3,2] row_mask:0xf bank_mask:0xf
	v_mov_b32_dpp v205, v205 quad_perm:[1,0,3,2] row_mask:0xf bank_mask:0xf
	v_cndmask_b32_e32 v206, v204, v188, vcc
	v_cndmask_b32_e32 v207, v189, v204, vcc
	v_cndmask_b32_e32 v208, v205, v190, vcc
	v_cndmask_b32_e32 v209, v191, v205, vcc
	v_cvt_pk_bf16_f32 v206, v206, v207
	v_cvt_pk_bf16_f32 v207, v208, v209
	global_store_dword v200, v206, s[20:21]
	global_store_dword v201, v207, s[20:21]
	v_mul_f32_e32 v188, 0xbfb8aa3b, v54
	v_mul_f32_e32 v189, 0xbfb8aa3b, v55
	v_mul_f32_e32 v190, 0xbfb8aa3b, v56
	v_mul_f32_e32 v191, 0xbfb8aa3b, v57
	v_exp_f32_e32 v188, v188
	v_exp_f32_e32 v189, v189
	v_exp_f32_e32 v190, v190
	v_exp_f32_e32 v191, v191
	v_add_u32_e32 v200, 0xb000, v32
	v_add_u32_e32 v201, 0xdc00, v32
	v_add_f32_e32 v188, 1.0, v188
	v_add_f32_e32 v189, 1.0, v189
	v_add_f32_e32 v190, 1.0, v190
	v_add_f32_e32 v191, 1.0, v191
	v_rcp_f32_e32 v188, v188
	v_rcp_f32_e32 v189, v189
	v_rcp_f32_e32 v190, v190
	v_rcp_f32_e32 v191, v191
	v_mul_f32_e32 v188, v54, v188
	v_mul_f32_e32 v189, v55, v189
	v_mul_f32_e32 v190, v56, v190
	v_mul_f32_e32 v191, v57, v191
	v_mul_f32_e32 v188, v38, v188
	v_mul_f32_e32 v189, v39, v189
	v_mul_f32_e32 v190, v40, v190
	v_mul_f32_e32 v191, v41, v191
	v_cndmask_b32_e32 v204, v188, v189, vcc
	v_cndmask_b32_e32 v205, v190, v191, vcc
	s_nop 1
	v_mov_b32_dpp v204, v204 quad_perm:[1,0,3,2] row_mask:0xf bank_mask:0xf
	v_mov_b32_dpp v205, v205 quad_perm:[1,0,3,2] row_mask:0xf bank_mask:0xf
	v_cndmask_b32_e32 v206, v204, v188, vcc
	v_cndmask_b32_e32 v207, v189, v204, vcc
	v_cndmask_b32_e32 v208, v205, v190, vcc
	v_cndmask_b32_e32 v209, v191, v205, vcc
	v_cvt_pk_bf16_f32 v206, v206, v207
	v_cvt_pk_bf16_f32 v207, v208, v209
	global_store_dword v200, v206, s[20:21]
	global_store_dword v201, v207, s[20:21]
	v_mul_f32_e32 v188, 0xbfb8aa3b, v58
	v_mul_f32_e32 v189, 0xbfb8aa3b, v59
	v_mul_f32_e32 v190, 0xbfb8aa3b, v60
	v_mul_f32_e32 v191, 0xbfb8aa3b, v61
	v_exp_f32_e32 v188, v188
	v_exp_f32_e32 v189, v189
	v_exp_f32_e32 v190, v190
	v_exp_f32_e32 v191, v191
	v_add_u32_e32 v200, 0x16000, v32
	v_add_u32_e32 v201, 0x18c00, v32
	v_add_f32_e32 v188, 1.0, v188
	v_add_f32_e32 v189, 1.0, v189
	v_add_f32_e32 v190, 1.0, v190
	v_add_f32_e32 v191, 1.0, v191
	v_rcp_f32_e32 v188, v188
	v_rcp_f32_e32 v189, v189
	v_rcp_f32_e32 v190, v190
	v_rcp_f32_e32 v191, v191
	v_mul_f32_e32 v188, v58, v188
	v_mul_f32_e32 v189, v59, v189
	v_mul_f32_e32 v190, v60, v190
	v_mul_f32_e32 v191, v61, v191
	v_mul_f32_e32 v188, v42, v188
	v_mul_f32_e32 v189, v43, v189
	v_mul_f32_e32 v190, v44, v190
	v_mul_f32_e32 v191, v45, v191
	v_cndmask_b32_e32 v204, v188, v189, vcc
	v_cndmask_b32_e32 v205, v190, v191, vcc
	s_nop 1
	v_mov_b32_dpp v204, v204 quad_perm:[1,0,3,2] row_mask:0xf bank_mask:0xf
	v_mov_b32_dpp v205, v205 quad_perm:[1,0,3,2] row_mask:0xf bank_mask:0xf
	v_cndmask_b32_e32 v206, v204, v188, vcc
	v_cndmask_b32_e32 v207, v189, v204, vcc
	v_cndmask_b32_e32 v208, v205, v190, vcc
	v_cndmask_b32_e32 v209, v191, v205, vcc
	v_cvt_pk_bf16_f32 v206, v206, v207
	v_cvt_pk_bf16_f32 v207, v208, v209
	global_store_dword v200, v206, s[20:21]
	global_store_dword v201, v207, s[20:21]
	v_mul_f32_e32 v188, 0xbfb8aa3b, v62
	v_mul_f32_e32 v189, 0xbfb8aa3b, v63
	v_mul_f32_e32 v190, 0xbfb8aa3b, v64
	v_mul_f32_e32 v191, 0xbfb8aa3b, v65
	v_exp_f32_e32 v188, v188
	v_exp_f32_e32 v189, v189
	v_exp_f32_e32 v190, v190
	v_exp_f32_e32 v191, v191
	v_add_u32_e32 v200, 0x21000, v32
	v_add_u32_e32 v201, 0x23c00, v32
	v_add_f32_e32 v188, 1.0, v188
	v_add_f32_e32 v189, 1.0, v189
	v_add_f32_e32 v190, 1.0, v190
	v_add_f32_e32 v191, 1.0, v191
	v_rcp_f32_e32 v188, v188
	v_rcp_f32_e32 v189, v189
	v_rcp_f32_e32 v190, v190
	v_rcp_f32_e32 v191, v191
	v_mul_f32_e32 v188, v62, v188
	v_mul_f32_e32 v189, v63, v189
	v_mul_f32_e32 v190, v64, v190
	v_mul_f32_e32 v191, v65, v191
	v_mul_f32_e32 v188, v46, v188
	v_mul_f32_e32 v189, v47, v189
	v_mul_f32_e32 v190, v48, v190
	v_mul_f32_e32 v191, v49, v191
	v_cndmask_b32_e32 v204, v188, v189, vcc
	v_cndmask_b32_e32 v205, v190, v191, vcc
	s_nop 1
	v_mov_b32_dpp v204, v204 quad_perm:[1,0,3,2] row_mask:0xf bank_mask:0xf
	v_mov_b32_dpp v205, v205 quad_perm:[1,0,3,2] row_mask:0xf bank_mask:0xf
	v_cndmask_b32_e32 v206, v204, v188, vcc
	v_cndmask_b32_e32 v207, v189, v204, vcc
	v_cndmask_b32_e32 v208, v205, v190, vcc
	v_cndmask_b32_e32 v209, v191, v205, vcc
	v_cvt_pk_bf16_f32 v206, v206, v207
	v_cvt_pk_bf16_f32 v207, v208, v209
	global_store_dword v200, v206, s[20:21]
	global_store_dword v201, v207, s[20:21]
	v_mul_f32_e32 v188, 0xbfb8aa3b, v16
	v_mul_f32_e32 v189, 0xbfb8aa3b, v17
	v_mul_f32_e32 v190, 0xbfb8aa3b, v18
	v_mul_f32_e32 v191, 0xbfb8aa3b, v19
	v_exp_f32_e32 v188, v188
	v_exp_f32_e32 v189, v189
	v_exp_f32_e32 v190, v190
	v_exp_f32_e32 v191, v191
	v_add_u32_e32 v200, 0x2c000, v32
	v_add_u32_e32 v201, 0x2ec00, v32
	v_add_f32_e32 v188, 1.0, v188
	v_add_f32_e32 v189, 1.0, v189
	v_add_f32_e32 v190, 1.0, v190
	v_add_f32_e32 v191, 1.0, v191
	v_rcp_f32_e32 v188, v188
	v_rcp_f32_e32 v189, v189
	v_rcp_f32_e32 v190, v190
	v_rcp_f32_e32 v191, v191
	v_mul_f32_e32 v188, v16, v188
	v_mul_f32_e32 v189, v17, v189
	v_mul_f32_e32 v190, v18, v190
	v_mul_f32_e32 v191, v19, v191
	v_mul_f32_e32 v188, v0, v188
	v_mul_f32_e32 v189, v1, v189
	v_mul_f32_e32 v190, v2, v190
	v_mul_f32_e32 v191, v3, v191
	v_cndmask_b32_e32 v204, v188, v189, vcc
	v_cndmask_b32_e32 v205, v190, v191, vcc
	s_nop 1
	v_mov_b32_dpp v204, v204 quad_perm:[1,0,3,2] row_mask:0xf bank_mask:0xf
	v_mov_b32_dpp v205, v205 quad_perm:[1,0,3,2] row_mask:0xf bank_mask:0xf
	v_cndmask_b32_e32 v206, v204, v188, vcc
	v_cndmask_b32_e32 v207, v189, v204, vcc
	v_cndmask_b32_e32 v208, v205, v190, vcc
	v_cndmask_b32_e32 v209, v191, v205, vcc
	v_cvt_pk_bf16_f32 v206, v206, v207
	v_cvt_pk_bf16_f32 v207, v208, v209
	global_store_dword v200, v206, s[20:21]
	global_store_dword v201, v207, s[20:21]
	v_mul_f32_e32 v188, 0xbfb8aa3b, v20
	v_mul_f32_e32 v189, 0xbfb8aa3b, v21
	v_mul_f32_e32 v190, 0xbfb8aa3b, v22
	v_mul_f32_e32 v191, 0xbfb8aa3b, v23
	v_exp_f32_e32 v188, v188
	v_exp_f32_e32 v189, v189
	v_exp_f32_e32 v190, v190
	v_exp_f32_e32 v191, v191
	v_add_u32_e32 v200, 0x37000, v32
	v_add_u32_e32 v201, 0x39c00, v32
	v_add_f32_e32 v188, 1.0, v188
	v_add_f32_e32 v189, 1.0, v189
	v_add_f32_e32 v190, 1.0, v190
	v_add_f32_e32 v191, 1.0, v191
	v_rcp_f32_e32 v188, v188
	v_rcp_f32_e32 v189, v189
	v_rcp_f32_e32 v190, v190
	v_rcp_f32_e32 v191, v191
	v_mul_f32_e32 v188, v20, v188
	v_mul_f32_e32 v189, v21, v189
	v_mul_f32_e32 v190, v22, v190
	v_mul_f32_e32 v191, v23, v191
	v_mul_f32_e32 v188, v4, v188
	v_mul_f32_e32 v189, v5, v189
	v_mul_f32_e32 v190, v6, v190
	v_mul_f32_e32 v191, v7, v191
	v_cndmask_b32_e32 v204, v188, v189, vcc
	v_cndmask_b32_e32 v205, v190, v191, vcc
	s_nop 1
	v_mov_b32_dpp v204, v204 quad_perm:[1,0,3,2] row_mask:0xf bank_mask:0xf
	v_mov_b32_dpp v205, v205 quad_perm:[1,0,3,2] row_mask:0xf bank_mask:0xf
	v_cndmask_b32_e32 v206, v204, v188, vcc
	v_cndmask_b32_e32 v207, v189, v204, vcc
	v_cndmask_b32_e32 v208, v205, v190, vcc
	v_cndmask_b32_e32 v209, v191, v205, vcc
	v_cvt_pk_bf16_f32 v206, v206, v207
	v_cvt_pk_bf16_f32 v207, v208, v209
	global_store_dword v200, v206, s[20:21]
	global_store_dword v201, v207, s[20:21]
	v_mul_f32_e32 v188, 0xbfb8aa3b, v24
	v_mul_f32_e32 v189, 0xbfb8aa3b, v25
	v_mul_f32_e32 v190, 0xbfb8aa3b, v26
	v_mul_f32_e32 v191, 0xbfb8aa3b, v27
	v_exp_f32_e32 v188, v188
	v_exp_f32_e32 v189, v189
	v_exp_f32_e32 v190, v190
	v_exp_f32_e32 v191, v191
	v_add_u32_e32 v200, 0x42000, v32
	v_add_u32_e32 v201, 0x44c00, v32
	v_add_f32_e32 v188, 1.0, v188
	v_add_f32_e32 v189, 1.0, v189
	v_add_f32_e32 v190, 1.0, v190
	v_add_f32_e32 v191, 1.0, v191
	v_rcp_f32_e32 v188, v188
	v_rcp_f32_e32 v189, v189
	v_rcp_f32_e32 v190, v190
	v_rcp_f32_e32 v191, v191
	v_mul_f32_e32 v188, v24, v188
	v_mul_f32_e32 v189, v25, v189
	v_mul_f32_e32 v190, v26, v190
	v_mul_f32_e32 v191, v27, v191
	v_mul_f32_e32 v188, v8, v188
	v_mul_f32_e32 v189, v9, v189
	v_mul_f32_e32 v190, v10, v190
	v_mul_f32_e32 v191, v11, v191
	v_cndmask_b32_e32 v204, v188, v189, vcc
	v_cndmask_b32_e32 v205, v190, v191, vcc
	s_nop 1
	v_mov_b32_dpp v204, v204 quad_perm:[1,0,3,2] row_mask:0xf bank_mask:0xf
	v_mov_b32_dpp v205, v205 quad_perm:[1,0,3,2] row_mask:0xf bank_mask:0xf
	v_cndmask_b32_e32 v206, v204, v188, vcc
	v_cndmask_b32_e32 v207, v189, v204, vcc
	v_cndmask_b32_e32 v208, v205, v190, vcc
	v_cndmask_b32_e32 v209, v191, v205, vcc
	v_cvt_pk_bf16_f32 v206, v206, v207
	v_cvt_pk_bf16_f32 v207, v208, v209
	global_store_dword v200, v206, s[20:21]
	global_store_dword v201, v207, s[20:21]
	v_mul_f32_e32 v188, 0xbfb8aa3b, v28
	v_mul_f32_e32 v189, 0xbfb8aa3b, v29
	v_mul_f32_e32 v190, 0xbfb8aa3b, v30
	v_mul_f32_e32 v191, 0xbfb8aa3b, v31
	v_exp_f32_e32 v188, v188
	v_exp_f32_e32 v189, v189
	v_exp_f32_e32 v190, v190
	v_exp_f32_e32 v191, v191
	v_add_u32_e32 v200, 0x4d000, v32
	v_add_u32_e32 v201, 0x4fc00, v32
	v_add_f32_e32 v188, 1.0, v188
	v_add_f32_e32 v189, 1.0, v189
	v_add_f32_e32 v190, 1.0, v190
	v_add_f32_e32 v191, 1.0, v191
	v_rcp_f32_e32 v188, v188
	v_rcp_f32_e32 v189, v189
	v_rcp_f32_e32 v190, v190
	v_rcp_f32_e32 v191, v191
	v_mul_f32_e32 v188, v28, v188
	v_mul_f32_e32 v189, v29, v189
	v_mul_f32_e32 v190, v30, v190
	v_mul_f32_e32 v191, v31, v191
	v_mul_f32_e32 v188, v12, v188
	v_mul_f32_e32 v189, v13, v189
	v_mul_f32_e32 v190, v14, v190
	v_mul_f32_e32 v191, v15, v191
	v_cndmask_b32_e32 v204, v188, v189, vcc
	v_cndmask_b32_e32 v205, v190, v191, vcc
	s_nop 1
	v_mov_b32_dpp v204, v204 quad_perm:[1,0,3,2] row_mask:0xf bank_mask:0xf
	v_mov_b32_dpp v205, v205 quad_perm:[1,0,3,2] row_mask:0xf bank_mask:0xf
	v_cndmask_b32_e32 v206, v204, v188, vcc
	v_cndmask_b32_e32 v207, v189, v204, vcc
	v_cndmask_b32_e32 v208, v205, v190, vcc
	v_cndmask_b32_e32 v209, v191, v205, vcc
	v_cvt_pk_bf16_f32 v206, v206, v207
	v_cvt_pk_bf16_f32 v207, v208, v209
	global_store_dword v200, v206, s[20:21]
	global_store_dword v201, v207, s[20:21]
	s_mov_b64 s[20:21], 0
	s_and_b64 vcc, exec, s[0:1]
	s_cbranch_vccz .LBB0_51
